# v74 + mixer-A items spread one per wave over waves 0-3 of all 256 workgroups (sample items on waves 4-5 of workgroups 0..15) instead of eight per workgroup on 132
# speedup vs baseline: 1.0061x; 1.0032x over previous
.LBB0_635:
	s_cmp_eq_u32 s98, 2
	s_cbranch_scc1 .Lp3be_ret
	s_cmpk_eq_i32 s80, 0x100
	s_cselect_b32 s33, 16, 0
	v_mov_b32_e32 v0, v179
	s_cmp_ge_i32 s83, s33
	s_cselect_b64 s[4:5], -1, 0
	v_readfirstlane_b32 s2, v0
	s_ashr_i32 s2, s2, 6
	s_cmpk_lg_u32 s80, 0x100
	s_cbranch_scc1 .Lmx_old
	s_cmp_lt_u32 s2, 4
	s_cbranch_scc0 .Lmx_hi
	s_lshl_b32 s28, s83, 2
	s_add_i32 s28, s28, s2
	s_branch .Lmx_go
.Lmx_hi:
	s_cmp_gt_u32 s2, 5
	s_cbranch_scc1 .LBB0_654
	s_cmp_gt_u32 s83, 15
	s_cbranch_scc1 .LBB0_654
	s_lshl_b32 s28, s83, 1
	s_add_i32 s28, s28, s2
	s_addk_i32 s28, 0x3fc
.Lmx_go:
	s_movk_i32 s29, 0x1000
	s_branch .Lmx_join
.Lmx_old:
	s_cmp_lt_i32 s83, s33
	s_cbranch_scc1 .LBB0_654
	s_sub_i32 s3, s83, s33
	s_lshl_b32 s3, s3, 3
	s_add_i32 s28, s2, s3
	s_cmpk_gt_i32 s28, 0x41f
	s_cbranch_scc1 .LBB0_654
	s_sub_i32 s2, s80, s33
	s_lshl_b32 s29, s2, 3
.Lmx_join:
	v_readlane_b32 s12, v254, 16
	v_readlane_b32 s13, v254, 17
	s_add_u32 s10, s12, 0x1000
	s_addc_u32 s11, s13, 0
	s_add_u32 s12, s12, 0x2000
	s_addc_u32 s13, s13, 0
	v_readlane_b32 s14, v254, 18
	v_readlane_b32 s15, v254, 19
	s_add_u32 s30, s74, 0x17203800
	s_addc_u32 s31, s75, 0
	s_lshl_b32 s14, s80, 12
	s_lshl_b32 s15, s33, 12
	v_readlane_b32 s36, v254, 32
	s_lshl_b32 s34, s28, 9
	s_sub_i32 s35, s14, s15
	v_readlane_b32 s50, v254, 46
	v_lshlrev_b32_e32 v0, 3, v0
	v_readlane_b32 s16, v254, 20
	v_readlane_b32 s17, v254, 21
	v_readlane_b32 s18, v254, 22
	v_readlane_b32 s19, v254, 23
	v_readlane_b32 s37, v254, 33
	v_readlane_b32 s38, v254, 34
	v_readlane_b32 s39, v254, 35
	v_readlane_b32 s40, v254, 36
	v_readlane_b32 s41, v254, 37
	v_readlane_b32 s42, v254, 38
	v_readlane_b32 s43, v254, 39
	v_readlane_b32 s44, v254, 40
	v_readlane_b32 s45, v254, 41
	v_readlane_b32 s51, v254, 47
	s_add_u32 s36, s50, 0xfffc8000
	v_and_b32_e32 v74, 0x1f8, v0
	s_mov_b64 s[2:3], 0x1000
	s_addc_u32 s37, s51, -1
	v_mov_b32_e32 v65, 0
	s_mov_b32 s15, 0
	s_mov_b32 s38, 0x94e0000
	s_mov_b32 s39, 0xe8dfd000
	s_movk_i32 s40, 0xd000
	s_mov_b32 s41, 0xe8dfe000
	s_movk_i32 s42, 0xe000
	s_mov_b32 s43, 0xe8dff000
	s_movk_i32 s44, 0xf000
	s_mov_b32 s45, 0xe8e00000
	s_mov_b64 s[16:17], 0x4000
	s_mov_b64 s[18:19], 0x8000
	v_readlane_b32 s20, v254, 24
	v_readlane_b32 s21, v254, 25
	v_readlane_b32 s22, v254, 26
	v_readlane_b32 s23, v254, 27
	v_readlane_b32 s24, v254, 28
	v_readlane_b32 s25, v254, 29
	v_readlane_b32 s26, v254, 30
	v_readlane_b32 s27, v254, 31
	v_readlane_b32 s46, v254, 42
	v_readlane_b32 s47, v254, 43
	v_readlane_b32 s48, v254, 44
	v_readlane_b32 s49, v254, 45
	s_branch .LBB0_639
